# k28: k27 + scan output block (cvt, addresses, 4 stores) interleaved into the last state-update MFMA group instead of sitting before the step-end barrier
# speedup vs baseline: 1.0020x; 1.0020x over previous
; #define LAS __attribute__((address_space(3)))
; __device__ __forceinline__ unsigned cvtpk(float lo, float hi) { unsigned r; asm volatile("v_cvt_pk_bf16_f32 %0, %1, %2" : "=v"(r) : "v"(lo), "v"(hi)); return r; }
; __device__ __forceinline__ bf16x8 cat(s16x4 a, s16x4 b) { return (bf16x8){a[0], a[1], a[2], a[3], b[0], b[1], b[2], b[3]}; }
; #define MF16(a, b, c) __builtin_amdgcn_mfma_f32_16x16x32_bf16((a), (b), (c), 0, 0, 0)
; #define SCHED() __builtin_amdgcn_sched_barrier(0)
; __device__ __forceinline__ void ret_item(LAS unsigned char* lds, const bf16_t* proj, bf16_t* OD, int b, int h, int dir, int vs, float lg2) {
;     ...
;             LDS_S(0, 0);
; #pragma unroll
;             for (int s = 0; s < 8; ++s) { if (s < 7) LDS_S((s + 1) & 1, s + 1); SCHED();
;                 const bf16x8 bq = cat(fq[s & 1][0], fq[s & 1][1]);
;                 __builtin_amdgcn_s_setprio(1); sa0 = MF16(fk0[s & 1], bq, sa0); sa1 = MF16(fk1[s & 1], bq, sa1); __builtin_amdgcn_s_setprio(0); SCHED(); }
;     ...
; #pragma unroll
;             for (int tt = 0; tt < 2; ++tt) { const f32x4 sv = tt ? sa1 : sa0; const int dt = dir ? (sjt0 + tt - sit) : (sit - sjt0 - tt);
;                 const float cs = dt <= 0 ? 1.f : dt == 1 ? c16 : dt == 2 ? c32 : c48; float w[4];
; #pragma unroll
;                 for (int r = 0; r < 4; ++r) { const bool on = dt > 0 || (dt == 0 && (dir ? (4 * g + r > l15) : (l15 >= 4 * g + r))); w[r] = on ? sv[r] * d4[r] * cs : 0.f; }
;                 u32x2 pkd; pkd.x = cvtpk(w[0], w[1]); pkd.y = cvtpk(w[2], w[3]);
;                 *(LAS u32x2*)(lds + SP + (16 * sit + l15) * RSS + (16 * (sjt0 + tt) + 4 * g) * 2) = pkd; }
;     ...
;         {   bf16x8 ca[2][4];
;     ...
;             LDS_C(0, 0);
; #pragma unroll
;             for (int s = 0; s < 8; ++s) { if (s < 7) LDS_C((s + 1) & 1, s + 1); SCHED();
;                 u32x4 bw; bw.x = cvtpk(st[2 * s][0], st[2 * s][1]); bw.y = cvtpk(st[2 * s][2], st[2 * s][3]); bw.z = cvtpk(st[2 * s + 1][0], st[2 * s + 1][1]); bw.w = cvtpk(st[2 * s + 1][2], st[2 * s + 1][3]);
;                 const bf16x8 bs = __builtin_bit_cast(bf16x8, bw);
;                 __builtin_amdgcn_s_setprio(1);
; #pragma unroll
;                 for (int it = 0; it < 4; ++it) acc[it] = MF16(bs, ca[s & 1][it], acc[it]);
;                 __builtin_amdgcn_s_setprio(0); SCHED(); }
.Lscan_pf_skip3:
	s_setprio 1
	s_waitcnt lgkmcnt(4)
	v_mfma_f32_16x16x32_bf16 v[108:111], v[120:123], v[116:119], v[108:111]
	s_waitcnt lgkmcnt(3)
	v_mfma_f32_16x16x32_bf16 v[104:107], v[124:127], v[116:119], v[104:107]
	s_setprio 0
	ds_read2_b64 v[116:119], v229 offset0:40 offset1:42
	ds_read_b128 v[120:123], v230 offset:37184
	ds_read_b128 v[124:127], v230 offset:46400
	s_setprio 1
	s_waitcnt lgkmcnt(4)
	v_mfma_f32_16x16x32_bf16 v[108:111], v[128:131], v[112:115], v[108:111]
	s_waitcnt lgkmcnt(3)
	v_mfma_f32_16x16x32_bf16 v[104:107], v[132:135], v[112:115], v[104:107]
	s_setprio 0
	ds_read2_b64 v[112:115], v229 offset0:48 offset1:50
	ds_read_b128 v[128:131], v230 offset:37248
	ds_read_b128 v[132:135], v230 offset:46464
	s_setprio 1
	s_waitcnt lgkmcnt(4)
	v_mfma_f32_16x16x32_bf16 v[108:111], v[120:123], v[116:119], v[108:111]
	s_waitcnt lgkmcnt(3)
	v_mfma_f32_16x16x32_bf16 v[104:107], v[124:127], v[116:119], v[104:107]
	s_setprio 0
	ds_read2_b64 v[116:119], v229 offset0:56 offset1:58
	ds_read_b128 v[120:123], v230 offset:37312
	ds_read_b128 v[124:127], v230 offset:46528
	s_setprio 1
	s_waitcnt lgkmcnt(4)
	v_mfma_f32_16x16x32_bf16 v[108:111], v[128:131], v[112:115], v[108:111]
	s_waitcnt lgkmcnt(3)
	v_mfma_f32_16x16x32_bf16 v[104:107], v[132:135], v[112:115], v[104:107]
	s_setprio 0
	s_setprio 1
	s_waitcnt lgkmcnt(1)
	v_mfma_f32_16x16x32_bf16 v[108:111], v[120:123], v[116:119], v[108:111]
	s_waitcnt lgkmcnt(0)
	v_mfma_f32_16x16x32_bf16 v[104:107], v[124:127], v[116:119], v[104:107]
	s_setprio 0
	s_nop 4
	v_mul_f32_e32 v108, v199, v108
	v_mul_f32_e32 v109, v200, v109
	v_mul_f32_e32 v110, v201, v110
	v_mul_f32_e32 v108, v206, v108
	v_mul_f32_e32 v109, v206, v109
	v_mul_f32_e32 v110, v206, v110
	v_mul_f32_e32 v111, v202, v111
	v_mul_f32_e32 v104, v199, v104
	v_mul_f32_e32 v105, v200, v105
	v_mul_f32_e32 v106, v201, v106
	v_cndmask_b32_e64 v108, 0, v108, s[38:39]
	v_cndmask_b32_e64 v109, 0, v109, s[40:41]
	v_cndmask_b32_e64 v110, 0, v110, s[42:43]
	v_mul_f32_e32 v111, v206, v111
	v_mul_f32_e32 v104, v207, v104
	v_mul_f32_e32 v105, v207, v105
	v_mul_f32_e32 v106, v207, v106
	v_mul_f32_e32 v107, v202, v107
	v_cndmask_b32_e64 v111, 0, v111, s[44:45]
	v_cvt_pk_bf16_f32 v108, v108, v109
	v_cvt_pk_bf16_f32 v109, v110, v111
	v_add_u32_e32 v110, s17, v205
	v_cndmask_b32_e64 v104, 0, v104, s[46:47]
	v_cndmask_b32_e64 v105, 0, v105, s[48:49]
	v_cndmask_b32_e64 v106, 0, v106, s[50:51]
	v_mul_f32_e32 v107, v207, v107
	ds_write_b64 v110, v[108:109]
	v_cndmask_b32_e64 v107, 0, v107, s[52:53]
	v_cvt_pk_bf16_f32 v104, v104, v105
	v_cvt_pk_bf16_f32 v105, v106, v107
	v_add_u32_e32 v106, s18, v205
	ds_write_b64 v106, v[104:105]
	ds_read_b128 v[104:107], v231
	ds_read_b128 v[108:111], v231 offset:64
	ds_read_b128 v[112:115], v231 offset:9216
	ds_read_b128 v[116:119], v231 offset:9280
	ds_read_b128 v[120:123], v231 offset:18432
	ds_read_b128 v[124:127], v231 offset:18496
	ds_read_b128 v[128:131], v231 offset:27648
	ds_read_b128 v[132:135], v231 offset:27712
	v_cvt_pk_bf16_f32 v136, v40, v41
	v_cvt_pk_bf16_f32 v137, v42, v43
	v_cvt_pk_bf16_f32 v138, v52, v53
	v_cvt_pk_bf16_f32 v139, v54, v55
	s_setprio 1
	s_waitcnt lgkmcnt(7)
	v_mfma_f32_16x16x32_bf16 v[104:107], v[136:139], v[104:107], 0
	s_waitcnt lgkmcnt(5)
	v_mfma_f32_16x16x32_bf16 v[112:115], v[136:139], v[112:115], 0
	s_waitcnt lgkmcnt(3)
	v_mfma_f32_16x16x32_bf16 v[120:123], v[136:139], v[120:123], 0
	s_waitcnt lgkmcnt(1)
	v_mfma_f32_16x16x32_bf16 v[128:131], v[136:139], v[128:131], 0
	s_setprio 0
	ds_read_b128 v[136:139], v231 offset:128
	ds_read_b128 v[140:143], v231 offset:9344
	ds_read_b128 v[144:147], v231 offset:18560
	ds_read_b128 v[148:151], v231 offset:27776
	v_cvt_pk_bf16_f32 v152, v48, v49
	v_cvt_pk_bf16_f32 v153, v50, v51
	v_cvt_pk_bf16_f32 v154, v44, v45
	v_cvt_pk_bf16_f32 v155, v46, v47
	s_setprio 1
	v_mfma_f32_16x16x32_bf16 v[104:107], v[152:155], v[108:111], v[104:107]
	v_mfma_f32_16x16x32_bf16 v[108:111], v[152:155], v[116:119], v[112:115]
	v_mfma_f32_16x16x32_bf16 v[112:115], v[152:155], v[124:127], v[120:123]
	s_waitcnt lgkmcnt(4)
	v_mfma_f32_16x16x32_bf16 v[116:119], v[152:155], v[132:135], v[128:131]
	s_setprio 0
	ds_read_b128 v[120:123], v231 offset:192
	ds_read_b128 v[124:127], v231 offset:9408
	ds_read_b128 v[128:131], v231 offset:18624
	ds_read_b128 v[132:135], v231 offset:27840
	v_cvt_pk_bf16_f32 v152, v68, v69
	v_cvt_pk_bf16_f32 v153, v70, v71
	v_cvt_pk_bf16_f32 v154, v64, v65
	v_cvt_pk_bf16_f32 v155, v66, v67
	s_setprio 1
	s_waitcnt lgkmcnt(7)
	v_mfma_f32_16x16x32_bf16 v[104:107], v[152:155], v[136:139], v[104:107]
	s_waitcnt lgkmcnt(6)
	v_mfma_f32_16x16x32_bf16 v[108:111], v[152:155], v[140:143], v[108:111]
	s_waitcnt lgkmcnt(5)
	v_mfma_f32_16x16x32_bf16 v[112:115], v[152:155], v[144:147], v[112:115]
	s_waitcnt lgkmcnt(4)
	v_mfma_f32_16x16x32_bf16 v[116:119], v[152:155], v[148:151], v[116:119]
	s_setprio 0
	ds_read_b128 v[136:139], v231 offset:256
	ds_read_b128 v[140:143], v231 offset:9472
	ds_read_b128 v[144:147], v231 offset:18688
	ds_read_b128 v[148:151], v231 offset:27904
	v_cvt_pk_bf16_f32 v152, v60, v61
	v_cvt_pk_bf16_f32 v153, v62, v63
	v_cvt_pk_bf16_f32 v154, v56, v57
	v_cvt_pk_bf16_f32 v155, v58, v59
	s_setprio 1
	s_waitcnt lgkmcnt(7)
	v_mfma_f32_16x16x32_bf16 v[104:107], v[152:155], v[120:123], v[104:107]
	s_waitcnt lgkmcnt(6)
	v_mfma_f32_16x16x32_bf16 v[108:111], v[152:155], v[124:127], v[108:111]
	s_waitcnt lgkmcnt(5)
	v_mfma_f32_16x16x32_bf16 v[112:115], v[152:155], v[128:131], v[112:115]
	s_waitcnt lgkmcnt(4)
; #define LAS __attribute__((address_space(3)))
; __device__ __forceinline__ unsigned cvtpk(float lo, float hi) { unsigned r; asm volatile("v_cvt_pk_bf16_f32 %0, %1, %2" : "=v"(r) : "v"(lo), "v"(hi)); return r; }
; __device__ __forceinline__ s16x4 trd(LAS unsigned char* p) { return __builtin_bit_cast(s16x4, __builtin_amdgcn_ds_read_tr16_b64_v4i16((LAS s16x4*)p)); }
; __device__ __forceinline__ bf16x8 cat(s16x4 a, s16x4 b) { return (bf16x8){a[0], a[1], a[2], a[3], b[0], b[1], b[2], b[3]}; }
; #define MF16(a, b, c) __builtin_amdgcn_mfma_f32_16x16x32_bf16((a), (b), (c), 0, 0, 0)
; __device__ __forceinline__ unsigned cvtpk(float lo, float hi) { unsigned r; asm volatile("v_cvt_pk_bf16_f32 %0, %1, %2" : "=v"(r) : "v"(lo), "v"(hi)); return r; }
; #define SCHED() __builtin_amdgcn_sched_barrier(0)
; __device__ __forceinline__ void ret_item(LAS unsigned char* lds, const bf16_t* proj, bf16_t* OD, int b, int h, int dir, int vs, float lg2) {
;     ...
;         {   bf16x8 ca[2][4];
;     ...
;             LDS_C(0, 0);
; #pragma unroll
;             for (int s = 0; s < 8; ++s) { if (s < 7) LDS_C((s + 1) & 1, s + 1); SCHED();
;                 u32x4 bw; bw.x = cvtpk(st[2 * s][0], st[2 * s][1]); bw.y = cvtpk(st[2 * s][2], st[2 * s][3]); bw.z = cvtpk(st[2 * s + 1][0], st[2 * s + 1][1]); bw.w = cvtpk(st[2 * s + 1][2], st[2 * s + 1][3]);
;                 const bf16x8 bs = __builtin_bit_cast(bf16x8, bw);
;                 __builtin_amdgcn_s_setprio(1);
; #pragma unroll
;                 for (int it = 0; it < 4; ++it) acc[it] = MF16(bs, ca[s & 1][it], acc[it]);
;                 __builtin_amdgcn_s_setprio(0); SCHED(); }
;     ...
;         bf16x8 bv[2], ia[2][4];
; #pragma unroll
;         for (int s = 0; s < 2; ++s) { bv[s] = cat(trd(pVt + 32 * s * RSV), trd(pVt + (32 * s + 4) * RSV));
; #pragma unroll
;             for (int it = 0; it < 4; ++it) ia[s][it] = *(const LAS bf16x8*)(pIs + 16 * it * RSS + 64 * s); }
;         s16x4 ua[2][4][2];
;     ...
;         LDS_U(0, 0);
;         SCHED();
; #pragma unroll
;         for (int it = 0; it < 4; ++it) { const int ex = dir ? 3 - it : it; const float cq = qdl * (ex == 0 ? 1.f : ex == 1 ? c16 : ex == 2 ? c32 : c48); acc[it] = acc[it] * cq; }
; #pragma unroll
;         for (int s = 0; s < 2; ++s)
; #pragma unroll
;             for (int it = 0; it < 4; ++it) acc[it] = MF16(bv[s], ia[s][it], acc[it]);
	v_mfma_f32_16x16x32_bf16 v[116:119], v[152:155], v[132:135], v[116:119]
	s_setprio 0
	ds_read_b128 v[120:123], v231 offset:320
	ds_read_b128 v[124:127], v231 offset:9536
	ds_read_b128 v[128:131], v231 offset:18752
	ds_read_b128 v[132:135], v231 offset:27968
	v_cvt_pk_bf16_f32 v152, v88, v89
	v_cvt_pk_bf16_f32 v153, v90, v91
	v_cvt_pk_bf16_f32 v154, v80, v81
	v_cvt_pk_bf16_f32 v155, v82, v83
	s_setprio 1
	s_waitcnt lgkmcnt(7)
	v_mfma_f32_16x16x32_bf16 v[104:107], v[152:155], v[136:139], v[104:107]
	s_waitcnt lgkmcnt(6)
	v_mfma_f32_16x16x32_bf16 v[108:111], v[152:155], v[140:143], v[108:111]
	s_waitcnt lgkmcnt(5)
	v_mfma_f32_16x16x32_bf16 v[112:115], v[152:155], v[144:147], v[112:115]
	s_waitcnt lgkmcnt(4)
	v_mfma_f32_16x16x32_bf16 v[116:119], v[152:155], v[148:151], v[116:119]
	s_setprio 0
	ds_read_b128 v[136:139], v231 offset:384
	ds_read_b128 v[140:143], v231 offset:9600
	ds_read_b128 v[144:147], v231 offset:18816
	ds_read_b128 v[148:151], v231 offset:28032
	v_cvt_pk_bf16_f32 v152, v76, v77
	v_cvt_pk_bf16_f32 v153, v78, v79
	v_cvt_pk_bf16_f32 v154, v72, v73
	v_cvt_pk_bf16_f32 v155, v74, v75
	s_setprio 1
	s_waitcnt lgkmcnt(7)
	v_mfma_f32_16x16x32_bf16 v[104:107], v[152:155], v[120:123], v[104:107]
	s_waitcnt lgkmcnt(6)
	v_mfma_f32_16x16x32_bf16 v[108:111], v[152:155], v[124:127], v[108:111]
	s_waitcnt lgkmcnt(5)
	v_mfma_f32_16x16x32_bf16 v[112:115], v[152:155], v[128:131], v[112:115]
	s_waitcnt lgkmcnt(4)
	v_mfma_f32_16x16x32_bf16 v[116:119], v[152:155], v[132:135], v[116:119]
	s_setprio 0
	ds_read_b128 v[120:123], v231 offset:448
	ds_read_b128 v[124:127], v231 offset:9664
	ds_read_b128 v[128:131], v231 offset:18880
	ds_read_b128 v[132:135], v231 offset:28096
	v_cvt_pk_bf16_f32 v152, v92, v93
	v_cvt_pk_bf16_f32 v153, v94, v95
	v_cvt_pk_bf16_f32 v154, v84, v85
	v_cvt_pk_bf16_f32 v155, v86, v87
	s_setprio 1
	s_waitcnt lgkmcnt(7)
	v_mfma_f32_16x16x32_bf16 v[104:107], v[152:155], v[136:139], v[104:107]
	s_waitcnt lgkmcnt(6)
	v_mfma_f32_16x16x32_bf16 v[108:111], v[152:155], v[140:143], v[108:111]
	s_waitcnt lgkmcnt(5)
	v_mfma_f32_16x16x32_bf16 v[112:115], v[152:155], v[144:147], v[112:115]
	s_waitcnt lgkmcnt(4)
	v_mfma_f32_16x16x32_bf16 v[116:119], v[152:155], v[148:151], v[116:119]
	s_setprio 0
	v_cvt_pk_bf16_f32 v136, v96, v97
	v_cvt_pk_bf16_f32 v137, v98, v99
	v_cvt_pk_bf16_f32 v138, v100, v101
	v_cvt_pk_bf16_f32 v139, v102, v103
	s_setprio 1
	s_waitcnt lgkmcnt(3)
	v_mfma_f32_16x16x32_bf16 v[104:107], v[136:139], v[120:123], v[104:107]
	s_waitcnt lgkmcnt(2)
	v_mfma_f32_16x16x32_bf16 v[108:111], v[136:139], v[124:127], v[108:111]
	s_waitcnt lgkmcnt(1)
	v_mfma_f32_16x16x32_bf16 v[112:115], v[136:139], v[128:131], v[112:115]
	s_waitcnt lgkmcnt(0)
	v_mfma_f32_16x16x32_bf16 v[116:119], v[136:139], v[132:135], v[116:119]
	s_setprio 0
	s_waitcnt lgkmcnt(0)
	s_barrier
	ds_read_b64_tr_b16 v[140:141], v232
	ds_read_b64_tr_b16 v[142:143], v232 offset:1088
	ds_read_b64_tr_b16 v[136:137], v232 offset:8704
	ds_read_b64_tr_b16 v[138:139], v232 offset:9792
	ds_read_b128 v[144:147], v233
	ds_read_b128 v[148:151], v233 offset:64
	ds_read_b128 v[152:155], v233 offset:2304
	ds_read_b128 v[156:159], v233 offset:2368
	ds_read_b128 v[236:239], v233 offset:4608
	ds_read_b128 v[240:243], v233 offset:4672
	ds_read_b128 v[244:247], v233 offset:6912
	ds_read_b128 v[248:251], v233 offset:6976
	v_add_u32_e32 v235, v204, v203
	ds_read_b64_tr_b16 v[128:129], v235 offset:36864
	ds_read_b64_tr_b16 v[130:131], v235 offset:39168
	ds_read_b64_tr_b16 v[126:127], v235 offset:39232
	ds_read_b64_tr_b16 v[124:125], v235 offset:36928
	ds_read_b64_tr_b16 v[132:133], v234 offset:36896
	ds_read_b64_tr_b16 v[134:135], v234 offset:39200
	ds_read_b64_tr_b16 v[122:123], v234 offset:39264
	ds_read_b64_tr_b16 v[120:121], v234 offset:36960
	v_pk_mul_f32 v[106:107], v[180:181], v[106:107]
	v_pk_mul_f32 v[104:105], v[178:179], v[104:105]
	v_pk_mul_f32 v[114:115], v[188:189], v[114:115]
	v_pk_mul_f32 v[112:113], v[186:187], v[112:113]
	s_waitcnt lgkmcnt(14)
	v_mfma_f32_16x16x32_bf16 v[104:107], v[140:143], v[144:147], v[104:107]
	v_mul_f32_e64 v110, v184, v110
	v_mul_f32_e64 v111, v185, v111
	v_pk_mul_f32 v[108:109], v[182:183], v[108:109]
	s_waitcnt lgkmcnt(11)
	v_mfma_f32_16x16x32_bf16 v[144:147], v[140:143], v[236:239], v[112:115]
	s_nop 2
	v_mul_f32_e64 v114, v192, v118
	v_mul_f32_e64 v115, v193, v119
	v_pk_mul_f32 v[112:113], v[190:191], v[116:117]
	v_mfma_f32_16x16x32_bf16 v[108:111], v[140:143], v[152:155], v[108:111]
	s_waitcnt lgkmcnt(9)
	v_mfma_f32_16x16x32_bf16 v[152:155], v[140:143], v[244:247], v[112:115]
	v_mfma_f32_16x16x32_bf16 v[116:119], v[136:139], v[148:151], v[104:107]
	v_mfma_f32_16x16x32_bf16 v[112:115], v[136:139], v[156:159], v[108:111]
	v_mfma_f32_16x16x32_bf16 v[108:111], v[136:139], v[240:243], v[144:147]
	s_waitcnt lgkmcnt(8)
; __device__ __forceinline__ unsigned cvtpk(float lo, float hi) { unsigned r; asm volatile("v_cvt_pk_bf16_f32 %0, %1, %2" : "=v"(r) : "v"(lo), "v"(hi)); return r; }
; __device__ __forceinline__ bf16x8 cat(s16x4 a, s16x4 b) { return (bf16x8){a[0], a[1], a[2], a[3], b[0], b[1], b[2], b[3]}; }
; #define MF16(a, b, c) __builtin_amdgcn_mfma_f32_16x16x32_bf16((a), (b), (c), 0, 0, 0)
; __device__ __forceinline__ unsigned cvtpk(float lo, float hi) { unsigned r; asm volatile("v_cvt_pk_bf16_f32 %0, %1, %2" : "=v"(r) : "v"(lo), "v"(hi)); return r; }
; #define SCHED() __builtin_amdgcn_sched_barrier(0)
; #define LDS_U(buf, u) do { _Pragma("unroll") for (int k = 0; k < 4; ++k) { LAS unsigned char* pb = ((k & 1) ? pKo : pKe) + 32 * ((u) >> 2) * RSQ + 32 * (4 * ((u) & 3) + k); ua[buf][k][0] = trd(pb); ua[buf][k][1] = trd(pb + 4 * RSQ); } } while (0)
; __device__ __forceinline__ void ret_item(LAS unsigned char* lds, const bf16_t* proj, bf16_t* OD, int b, int h, int dir, int vs, float lg2) {
;     ...
;         for (int it = 0; it < 4; ++it) { const int ex = dir ? 3 - it : it; const float cq = qdl * (ex == 0 ? 1.f : ex == 1 ? c16 : ex == 2 ? c32 : c48); acc[it] = acc[it] * cq; }
; #pragma unroll
;         for (int s = 0; s < 2; ++s)
; #pragma unroll
;             for (int it = 0; it < 4; ++it) acc[it] = MF16(bv[s], ia[s][it], acc[it]);
;         SCHED();
; #pragma unroll
;         for (int i = 0; i < 16; ++i) st[i] = st[i] * cd;
;         bf16x8 bvd[2];
; #pragma unroll
;         for (int s = 0; s < 2; ++s) { const float ck = (dir ? s : 1 - s) ? c32 : 1.f; float e[8];
; #pragma unroll
;             for (int jj = 0; jj < 8; ++jj) e[jj] = bf2f((unsigned short)bv[s][jj]) * (kd8[jj] * ck);
;             u32x4 bw; bw.x = cvtpk(e[0], e[1]); bw.y = cvtpk(e[2], e[3]); bw.z = cvtpk(e[4], e[5]); bw.w = cvtpk(e[6], e[7]);
;             bvd[s] = __builtin_bit_cast(bf16x8, bw); }
; #pragma unroll
;         for (int u = 0; u < 8; ++u) { if (u < 7) LDS_U((u + 1) & 1, u + 1); SCHED();
;             __builtin_amdgcn_s_setprio(1);
; #pragma unroll
;             for (int k = 0; k < 4; ++k) st[4 * (u & 3) + k] = MF16(cat(ua[u & 1][k][0], ua[u & 1][k][1]), bvd[u >> 2], st[4 * (u & 3) + k]);
	v_mfma_f32_16x16x32_bf16 v[104:107], v[136:139], v[248:251], v[152:155]
	v_mov_b32_e32 v165, v164
	s_nop 1
	v_pk_mul_f32 v[154:155], v[164:165], v[46:47]
	v_pk_mul_f32 v[152:153], v[174:175], v[44:45]
	v_pk_mul_f32 v[46:47], v[164:165], v[70:71]
	v_pk_mul_f32 v[44:45], v[174:175], v[68:69]
	v_pk_mul_f32 v[158:159], v[164:165], v[58:59]
	v_pk_mul_f32 v[156:157], v[174:175], v[56:57]
	v_pk_mul_f32 v[70:71], v[164:165], v[82:83]
	v_pk_mul_f32 v[68:69], v[174:175], v[80:81]
	v_pk_mul_f32 v[82:83], v[164:165], v[78:79]
	v_pk_mul_f32 v[80:81], v[174:175], v[76:77]
	v_pk_mul_f32 v[58:59], v[164:165], v[94:95]
	v_pk_mul_f32 v[56:57], v[174:175], v[92:93]
	v_pk_mul_f32 v[78:79], v[164:165], v[86:87]
	v_pk_mul_f32 v[76:77], v[174:175], v[84:85]
	v_lshlrev_b32_e32 v84, 16, v140
	v_and_b32_e32 v85, 0xffff0000, v140
	v_lshlrev_b32_e32 v86, 16, v141
	v_and_b32_e32 v87, 0xffff0000, v141
	v_lshlrev_b32_e32 v92, 16, v142
	v_and_b32_e32 v93, 0xffff0000, v142
	v_lshlrev_b32_e32 v94, 16, v143
	v_and_b32_e32 v95, 0xffff0000, v143
	v_mul_f32_e32 v84, v208, v84
	v_mul_f32_e32 v85, v209, v85
	v_mul_f32_e32 v86, v210, v86
	v_mul_f32_e32 v87, v211, v87
	v_mul_f32_e32 v92, v212, v92
	v_mul_f32_e32 v93, v213, v93
	v_mul_f32_e32 v94, v214, v94
	v_mul_f32_e32 v95, v215, v95
	v_pk_mul_f32 v[146:147], v[164:165], v[50:51]
	v_pk_mul_f32 v[144:145], v[174:175], v[48:49]
	v_pk_mul_f32 v[50:51], v[164:165], v[90:91]
	v_pk_mul_f32 v[48:49], v[174:175], v[88:89]
	v_pk_mul_f32 v[90:91], v[164:165], v[74:75]
	v_pk_mul_f32 v[88:89], v[174:175], v[72:73]
	v_pk_mul_f32 v[74:75], v[164:165], v[98:99]
	v_pk_mul_f32 v[72:73], v[174:175], v[96:97]
	v_cvt_pk_bf16_f32 v84, v84, v85
	v_cvt_pk_bf16_f32 v85, v86, v87
	v_cvt_pk_bf16_f32 v86, v92, v93
	v_cvt_pk_bf16_f32 v87, v94, v95
	v_lshlrev_b32_e32 v92, 16, v136
	v_and_b32_e32 v93, 0xffff0000, v136
	v_lshlrev_b32_e32 v94, 16, v137
	v_and_b32_e32 v95, 0xffff0000, v137
	v_lshlrev_b32_e32 v96, 16, v138
	v_and_b32_e32 v97, 0xffff0000, v138
	v_lshlrev_b32_e32 v98, 16, v139
	v_and_b32_e32 v99, 0xffff0000, v139
	v_mul_f32_e32 v92, v216, v92
	v_mul_f32_e32 v93, v217, v93
	v_mul_f32_e32 v94, v218, v94
	v_mul_f32_e32 v95, v219, v95
	v_mul_f32_e32 v96, v220, v96
	v_mul_f32_e32 v97, v221, v97
	v_mul_f32_e32 v98, v222, v98
	v_mul_f32_e32 v99, v223, v99
	v_pk_mul_f32 v[150:151], v[164:165], v[62:63]
	v_pk_mul_f32 v[148:149], v[174:175], v[60:61]
	v_pk_mul_f32 v[62:63], v[164:165], v[102:103]
	v_pk_mul_f32 v[60:61], v[174:175], v[100:101]
	v_cvt_pk_bf16_f32 v100, v92, v93
	v_cvt_pk_bf16_f32 v101, v94, v95
	v_cvt_pk_bf16_f32 v102, v96, v97
	v_cvt_pk_bf16_f32 v103, v98, v99
	ds_read_b64_tr_b16 v[92:93], v235 offset:36992
	ds_read_b64_tr_b16 v[94:95], v235 offset:39296
	ds_read_b64_tr_b16 v[96:97], v234 offset:37024
	ds_read_b64_tr_b16 v[98:99], v234 offset:39328
	ds_read_b64_tr_b16 v[136:137], v235 offset:37056
	ds_read_b64_tr_b16 v[138:139], v235 offset:39360
	ds_read_b64_tr_b16 v[140:141], v234 offset:37088
	ds_read_b64_tr_b16 v[142:143], v234 offset:39392
	v_pk_mul_f32 v[42:43], v[164:165], v[42:43]
	v_pk_mul_f32 v[40:41], v[174:175], v[40:41]
	v_pk_mul_f32 v[54:55], v[164:165], v[54:55]
	v_pk_mul_f32 v[52:53], v[174:175], v[52:53]
	v_pk_mul_f32 v[66:67], v[164:165], v[66:67]
	v_pk_mul_f32 v[64:65], v[174:175], v[64:65]
	s_setprio 1
	s_waitcnt lgkmcnt(14)
	v_mfma_f32_16x16x32_bf16 v[40:43], v[128:131], v[84:87], v[40:43]
	s_waitcnt lgkmcnt(10)
	v_mfma_f32_16x16x32_bf16 v[52:55], v[132:135], v[84:87], v[52:55]
	v_mfma_f32_16x16x32_bf16 v[124:127], v[124:127], v[84:87], v[144:147]
	s_waitcnt lgkmcnt(8)
	v_mfma_f32_16x16x32_bf16 v[120:123], v[120:123], v[84:87], v[152:155]
	s_setprio 0
	ds_read_b64_tr_b16 v[128:129], v235 offset:37120
	ds_read_b64_tr_b16 v[130:131], v235 offset:39424
	ds_read_b64_tr_b16 v[134:135], v235 offset:39488
	ds_read_b64_tr_b16 v[132:133], v235 offset:37184
	ds_read_b64_tr_b16 v[144:145], v234 offset:37152
	ds_read_b64_tr_b16 v[146:147], v234 offset:39456
	ds_read_b64_tr_b16 v[154:155], v234 offset:39520
	ds_read_b64_tr_b16 v[152:153], v234 offset:37216
	s_setprio 1
	s_waitcnt lgkmcnt(14)
	v_mfma_f32_16x16x32_bf16 v[92:95], v[92:95], v[84:87], v[44:47]
	s_waitcnt lgkmcnt(12)
	v_mfma_f32_16x16x32_bf16 v[64:67], v[96:99], v[84:87], v[64:67]
	s_waitcnt lgkmcnt(10)
	v_mfma_f32_16x16x32_bf16 v[96:99], v[136:139], v[84:87], v[148:151]
	s_waitcnt lgkmcnt(8)
	v_mfma_f32_16x16x32_bf16 v[136:139], v[140:143], v[84:87], v[156:159]
	s_setprio 0
	ds_read_b64_tr_b16 v[44:45], v235 offset:37248
	ds_read_b64_tr_b16 v[46:47], v235 offset:39552
	ds_read_b64_tr_b16 v[142:143], v235 offset:39616
	ds_read_b64_tr_b16 v[140:141], v235 offset:37312
	ds_read_b64_tr_b16 v[148:149], v234 offset:37280
	ds_read_b64_tr_b16 v[150:151], v234 offset:39584
	ds_read_b64_tr_b16 v[158:159], v234 offset:39648
	ds_read_b64_tr_b16 v[156:157], v234 offset:37344
	s_setprio 1
	s_waitcnt lgkmcnt(14)
; __device__ __forceinline__ unsigned cvtpk(float lo, float hi) { unsigned r; asm volatile("v_cvt_pk_bf16_f32 %0, %1, %2" : "=v"(r) : "v"(lo), "v"(hi)); return r; }
; __device__ __forceinline__ bf16x8 cat(s16x4 a, s16x4 b) { return (bf16x8){a[0], a[1], a[2], a[3], b[0], b[1], b[2], b[3]}; }
; #define MF16(a, b, c) __builtin_amdgcn_mfma_f32_16x16x32_bf16((a), (b), (c), 0, 0, 0)
; #define RBAR() do { asm volatile("s_waitcnt lgkmcnt(0)" ::: "memory"); __builtin_amdgcn_s_barrier(); asm volatile("" ::: "memory"); } while (0)
; __device__ __forceinline__ unsigned cvtpk(float lo, float hi) { unsigned r; asm volatile("v_cvt_pk_bf16_f32 %0, %1, %2" : "=v"(r) : "v"(lo), "v"(hi)); return r; }
; #define SCHED() __builtin_amdgcn_sched_barrier(0)
; #define LDS_U(buf, u) do { _Pragma("unroll") for (int k = 0; k < 4; ++k) { LAS unsigned char* pb = ((k & 1) ? pKo : pKe) + 32 * ((u) >> 2) * RSQ + 32 * (4 * ((u) & 3) + k); ua[buf][k][0] = trd(pb); ua[buf][k][1] = trd(pb + 4 * RSQ); } } while (0)
; __device__ __forceinline__ void ret_item(LAS unsigned char* lds, const bf16_t* proj, bf16_t* OD, int b, int h, int dir, int vs, float lg2) {
;     ...
;         for (int u = 0; u < 8; ++u) { if (u < 7) LDS_U((u + 1) & 1, u + 1); SCHED();
;             __builtin_amdgcn_s_setprio(1);
; #pragma unroll
;             for (int k = 0; k < 4; ++k) st[4 * (u & 3) + k] = MF16(cat(ua[u & 1][k][0], ua[u & 1][k][1]), bvd[u >> 2], st[4 * (u & 3) + k]);
;             __builtin_amdgcn_s_setprio(0); SCHED(); }
;     ...
; #pragma unroll
;         for (int it = 0; it < 4; ++it) { u32x2 w; w.x = cvtpk(acc[it][0], acc[it][1]); w.y = cvtpk(acc[it][2], acc[it][3]); *(u32x2*)(Og + (t0 + 16 * it + l15) * 4096) = w; }
;         RBAR();
	v_mfma_f32_16x16x32_bf16 v[128:131], v[128:131], v[84:87], v[48:51]
	s_waitcnt lgkmcnt(10)
	v_mfma_f32_16x16x32_bf16 v[144:147], v[144:147], v[84:87], v[68:71]
	v_mfma_f32_16x16x32_bf16 v[132:135], v[132:135], v[84:87], v[80:83]
	s_waitcnt lgkmcnt(8)
	v_mfma_f32_16x16x32_bf16 v[152:155], v[152:155], v[84:87], v[88:91]
	s_setprio 0
	ds_read_b64_tr_b16 v[48:49], v235 offset:55296
	ds_read_b64_tr_b16 v[50:51], v235 offset:57600
	ds_read_b64_tr_b16 v[70:71], v235 offset:57664
	ds_read_b64_tr_b16 v[68:69], v235 offset:55360
	ds_read_b64_tr_b16 v[80:81], v234 offset:55328
	ds_read_b64_tr_b16 v[82:83], v234 offset:57632
	ds_read_b64_tr_b16 v[90:91], v234 offset:57696
	ds_read_b64_tr_b16 v[88:89], v234 offset:55392
	s_setprio 1
	s_waitcnt lgkmcnt(14)
	v_mfma_f32_16x16x32_bf16 v[236:239], v[44:47], v[84:87], v[56:59]
	s_waitcnt lgkmcnt(10)
	v_mfma_f32_16x16x32_bf16 v[148:151], v[148:151], v[84:87], v[76:79]
	v_mfma_f32_16x16x32_bf16 v[140:143], v[140:143], v[84:87], v[72:75]
	s_waitcnt lgkmcnt(8)
	v_mfma_f32_16x16x32_bf16 v[156:159], v[156:159], v[84:87], v[60:63]
	s_setprio 0
	ds_read_b64_tr_b16 v[56:57], v235 offset:55424
	ds_read_b64_tr_b16 v[58:59], v235 offset:57728
	ds_read_b64_tr_b16 v[62:63], v235 offset:57792
	ds_read_b64_tr_b16 v[60:61], v235 offset:55488
	ds_read_b64_tr_b16 v[72:73], v234 offset:55456
	ds_read_b64_tr_b16 v[74:75], v234 offset:57760
	ds_read_b64_tr_b16 v[78:79], v234 offset:57824
	ds_read_b64_tr_b16 v[76:77], v234 offset:55520
	s_setprio 1
	s_waitcnt lgkmcnt(14)
	v_mfma_f32_16x16x32_bf16 v[40:43], v[48:51], v[100:103], v[40:43]
	s_waitcnt lgkmcnt(10)
	v_mfma_f32_16x16x32_bf16 v[52:55], v[80:83], v[100:103], v[52:55]
	v_mfma_f32_16x16x32_bf16 v[48:51], v[68:71], v[100:103], v[124:127]
	s_waitcnt lgkmcnt(8)
	v_mfma_f32_16x16x32_bf16 v[44:47], v[88:91], v[100:103], v[120:123]
	s_setprio 0
	ds_read_b64_tr_b16 v[80:81], v235 offset:55552
	ds_read_b64_tr_b16 v[82:83], v235 offset:57856
	ds_read_b64_tr_b16 v[86:87], v235 offset:57920
	ds_read_b64_tr_b16 v[84:85], v235 offset:55616
	ds_read_b64_tr_b16 v[120:121], v234 offset:55584
	ds_read_b64_tr_b16 v[122:123], v234 offset:57888
	ds_read_b64_tr_b16 v[126:127], v234 offset:57952
	ds_read_b64_tr_b16 v[124:125], v234 offset:55648
	s_setprio 1
	s_waitcnt lgkmcnt(14)
	v_mfma_f32_16x16x32_bf16 v[68:71], v[56:59], v[100:103], v[92:95]
	s_waitcnt lgkmcnt(10)
	v_mfma_f32_16x16x32_bf16 v[64:67], v[72:75], v[100:103], v[64:67]
	v_mfma_f32_16x16x32_bf16 v[60:63], v[60:63], v[100:103], v[96:99]
	s_waitcnt lgkmcnt(8)
	v_mfma_f32_16x16x32_bf16 v[56:59], v[76:79], v[100:103], v[136:139]
	s_setprio 0
	ds_read_b64_tr_b16 v[92:93], v235 offset:55680
	ds_read_b64_tr_b16 v[94:95], v235 offset:57984
	ds_read_b64_tr_b16 v[98:99], v235 offset:58048
	ds_read_b64_tr_b16 v[96:97], v235 offset:55744
	ds_read_b64_tr_b16 v[136:137], v234 offset:55712
	ds_read_b64_tr_b16 v[138:139], v234 offset:58016
	ds_read_b64_tr_b16 v[242:243], v234 offset:58080
	ds_read_b64_tr_b16 v[240:241], v234 offset:55776
	s_setprio 1
	s_waitcnt lgkmcnt(14)
	v_mfma_f32_16x16x32_bf16 v[88:91], v[80:83], v[100:103], v[128:131]
	v_lshl_or_b32 v176, v176, 18, v224
	v_cvt_pk_bf16_f32 v116, v116, v117
	v_cvt_pk_bf16_f32 v117, v118, v119
	v_lshl_add_u64 v[118:119], v[176:177], 1, v[160:161]
	global_store_dwordx2 v[118:119], v[116:117], off
	s_waitcnt lgkmcnt(10)
	v_mfma_f32_16x16x32_bf16 v[80:83], v[120:123], v[100:103], v[144:147]
	v_mfma_f32_16x16x32_bf16 v[76:79], v[84:87], v[100:103], v[132:135]
	v_cvt_pk_bf16_f32 v112, v112, v113
	v_cvt_pk_bf16_f32 v113, v114, v115
	v_ashrrev_i32_e32 v115, 31, v176
	v_mov_b32_e32 v114, v176
	v_lshl_add_u64 v[114:115], v[114:115], 1, v[160:161]
	s_mov_b32 s20, 0x20000
	v_add_co_u32_e32 v116, vcc, s20, v114
	s_mov_b32 s20, 0x40000
	s_nop 0
	v_addc_co_u32_e32 v117, vcc, 0, v115, vcc
	global_store_dwordx2 v[116:117], v[112:113], off
	s_waitcnt lgkmcnt(8)
	v_mfma_f32_16x16x32_bf16 v[72:75], v[124:127], v[100:103], v[152:155]
	s_setprio 0
	s_setprio 1
	v_cvt_pk_bf16_f32 v108, v108, v109
	v_cvt_pk_bf16_f32 v109, v110, v111
	v_add_co_u32_e32 v110, vcc, s20, v114
	s_add_i32 s19, s19, -1
	s_nop 0
	v_addc_co_u32_e32 v111, vcc, 0, v115, vcc
	global_store_dwordx2 v[110:111], v[108:109], off
	s_waitcnt lgkmcnt(6)
	v_mfma_f32_16x16x32_bf16 v[92:95], v[92:95], v[100:103], v[236:239]
	v_cvt_pk_bf16_f32 v104, v104, v105
	v_cvt_pk_bf16_f32 v105, v106, v107
	v_add_co_u32_e32 v106, vcc, s65, v114
	s_add_i32 s16, s16, 1
	s_nop 0
	v_addc_co_u32_e32 v107, vcc, 0, v115, vcc
	global_store_dwordx2 v[106:107], v[104:105], off
	s_waitcnt lgkmcnt(2)
	v_mfma_f32_16x16x32_bf16 v[84:87], v[136:139], v[100:103], v[148:151]
	v_mfma_f32_16x16x32_bf16 v[96:99], v[96:99], v[100:103], v[140:143]
	s_waitcnt lgkmcnt(0)
	v_mfma_f32_16x16x32_bf16 v[100:103], v[240:243], v[100:103], v[156:159]
	s_setprio 0
	s_waitcnt lgkmcnt(0)
	s_barrier
	s_cmp_lg_u32 s19, -2
	s_cbranch_scc0 .LBB0_138
